# e19: hand-written final RMSNorm - row loads batched and issued two rows ahead, gain in registers
# baseline (speedup 1.0000x reference)
; __device__ __forceinline__ float row_scale_any(const float* ssq, const float* ssqS, int row) { return row < MP ? pg8::row_scale(ssq, row) : sk::row_scale_s(ssqS, row - MP); }
; __device__ __forceinline__ f32x4 ldx4(const bf16* p) { const u32x2 w = *(const u32x2*)p; return (f32x4){__uint_as_float(w.x << 16), __uint_as_float(w.x & 0xffff0000u), __uint_as_float(w.y << 16), __uint_as_float(w.y & 0xffff0000u)}; }
; #define PHASE_SYNC(id) do { if ((id) != lo) xcd_barrier(bar); } while (0)
; __device__ __forceinline__ float row_scale(const float* ssq, int row) { const f32x4 a = *(const f32x4*)(ssq + (size_t)row * 8), b = *(const f32x4*)(ssq + (size_t)row * 8 + 4);
;     return __builtin_amdgcn_rsqf((((a[0] + a[1]) + (a[2] + a[3])) + ((b[0] + b[1]) + (b[2] + b[3]))) * (1.0f / 2048.0f) + 1e-6f); }
; __global__ void __launch_bounds__(512, 2) fwd_kernel(Args a) {
;     ...
;     if (SITE(14) && PHASE_ON(41)) { const int layer = 0;
;         PHASE_SYNC(41); PH_PTRS
;         const float* ssq = SSQ + (size_t)8 * M * 8; const float* gf = ap->in[I_NFIN];
;         for (int m = gw; m < M; m += ngw) { const float rs = row_scale_any(ssq, SSQS + (size_t)8 * 16384, m); float* dst = m < MP ? out + OFF_Y_P + (size_t)m * D : out + OFF_Y_S + (size_t)(m - MP) * D;
; #pragma unroll
;             for (int j = 0; j < 8; ++j) { const int c = j * 256 + lane * 4; *(f32x4*)(dst + c) = ldx4(XB + (size_t)m * D + c) * rs * *(const f32x4*)(gf + c); } } }
.LBB0_2881:
	s_lshl_b32 s2, s96, 3
	v_readfirstlane_b32 s0, v0
	s_ashr_i32 s1, s0, 6
	s_add_i32 s0, s1, s2
	s_cmpk_gt_i32 s0, 0x40ff
	s_cbranch_scc1 .LBB0_2890
	s_load_dwordx2 s[4:5], s[94:95], 0xf8
	s_load_dwordx2 s[6:7], s[94:95], 0x100
	s_load_dwordx2 s[8:9], s[94:95], 0x40
	v_and_b32_e32 v1, 63, v0
	v_lshlrev_b32_e32 v2, 3, v1
	v_lshlrev_b32_e32 v3, 4, v1
	v_mov_b32_e32 v4, 0
	v_mov_b32_e32 v5, 0x358637bd
	v_and_b32_e32 v6, 15, v1
	v_lshlrev_b32_e32 v6, 4, v6
	s_lshl_b32 s10, s76, 3
	s_waitcnt lgkmcnt(0)
	s_add_u32 s12, s8, 0x1000
	s_addc_u32 s13, s9, 0
	global_load_dwordx4 v[8:11], v3, s[8:9]
	global_load_dwordx4 v[12:15], v3, s[8:9] offset:1024
	global_load_dwordx4 v[16:19], v3, s[8:9] offset:2048
	global_load_dwordx4 v[20:23], v3, s[8:9] offset:3072
	global_load_dwordx4 v[24:27], v3, s[12:13]
	global_load_dwordx4 v[28:31], v3, s[12:13] offset:1024
	global_load_dwordx4 v[32:35], v3, s[12:13] offset:2048
	global_load_dwordx4 v[36:39], v3, s[12:13] offset:3072
	s_add_u32 s22, s6, 0x41c10000
	s_addc_u32 s23, s7, 0
	s_add_u32 s24, s6, 0x41e80000
	s_addc_u32 s25, s7, 0
	s_add_u32 s6, s6, 0x20200000
	s_addc_u32 s7, s7, 0
	s_cmpk_gt_i32 s0, 0x3fff
	s_cbranch_scc1 .Lfn_sample
	s_lshl_b32 s14, s0, 5
	s_add_u32 s16, s22, s14
	s_addc_u32 s17, s23, 0
	s_lshl_b32 s14, s0, 12
	s_add_u32 s18, s6, s14
	s_addc_u32 s19, s7, 0
	global_load_dwordx4 v[72:75], v4, s[16:17]
	global_load_dwordx4 v[76:79], v4, s[16:17] offset:16
	global_load_dwordx2 v[40:41], v2, s[18:19]
	global_load_dwordx2 v[42:43], v2, s[18:19] offset:512
	global_load_dwordx2 v[44:45], v2, s[18:19] offset:1024
	global_load_dwordx2 v[46:47], v2, s[18:19] offset:1536
	global_load_dwordx2 v[48:49], v2, s[18:19] offset:2048
	global_load_dwordx2 v[50:51], v2, s[18:19] offset:2560
	global_load_dwordx2 v[52:53], v2, s[18:19] offset:3072
	global_load_dwordx2 v[54:55], v2, s[18:19] offset:3584
	s_add_i32 s1, s0, s10
	s_cmpk_gt_i32 s1, 0x3fff
	s_cbranch_scc1 .Lfn_pre1
	s_lshl_b32 s14, s1, 5
	s_add_u32 s16, s22, s14
	s_addc_u32 s17, s23, 0
	s_lshl_b32 s14, s1, 12
	s_add_u32 s18, s6, s14
	s_addc_u32 s19, s7, 0
	global_load_dwordx4 v[80:83], v4, s[16:17]
	global_load_dwordx4 v[84:87], v4, s[16:17] offset:16
	global_load_dwordx2 v[56:57], v2, s[18:19]
	global_load_dwordx2 v[58:59], v2, s[18:19] offset:512
	global_load_dwordx2 v[60:61], v2, s[18:19] offset:1024
	global_load_dwordx2 v[62:63], v2, s[18:19] offset:1536
	global_load_dwordx2 v[64:65], v2, s[18:19] offset:2048
	global_load_dwordx2 v[66:67], v2, s[18:19] offset:2560
	global_load_dwordx2 v[68:69], v2, s[18:19] offset:3072
	global_load_dwordx2 v[70:71], v2, s[18:19] offset:3584
	s_waitcnt vmcnt(10)
.Lfn_pre1:
.Lfn_loop:
.Lfn_body0:
	s_add_i32 s1, s0, s10
	s_cmpk_gt_i32 s1, 0x3fff
	s_cbranch_scc1 .Lfn_w0_0
	s_waitcnt vmcnt(18)
	s_branch .Lfn_wd_0

; __device__ __forceinline__ float row_scale_any(const float* ssq, const float* ssqS, int row) { return row < MP ? pg8::row_scale(ssq, row) : sk::row_scale_s(ssqS, row - MP); }
; __device__ __forceinline__ f32x4 ldx4(const bf16* p) { const u32x2 w = *(const u32x2*)p; return (f32x4){__uint_as_float(w.x << 16), __uint_as_float(w.x & 0xffff0000u), __uint_as_float(w.y << 16), __uint_as_float(w.y & 0xffff0000u)}; }
; __device__ __forceinline__ float row_scale(const float* ssq, int row) { const f32x4 a = *(const f32x4*)(ssq + (size_t)row * 8), b = *(const f32x4*)(ssq + (size_t)row * 8 + 4);
;     return __builtin_amdgcn_rsqf((((a[0] + a[1]) + (a[2] + a[3])) + ((b[0] + b[1]) + (b[2] + b[3]))) * (1.0f / 2048.0f) + 1e-6f); }
; __global__ void __launch_bounds__(512, 2) fwd_kernel(Args a) {
;     ...
;         for (int m = gw; m < M; m += ngw) { const float rs = row_scale_any(ssq, SSQS + (size_t)8 * 16384, m); float* dst = m < MP ? out + OFF_Y_P + (size_t)m * D : out + OFF_Y_S + (size_t)(m - MP) * D;
; #pragma unroll
;             for (int j = 0; j < 8; ++j) { const int c = j * 256 + lane * 4; *(f32x4*)(dst + c) = ldx4(XB + (size_t)m * D + c) * rs * *(const f32x4*)(gf + c); } } }
.Lfn_wd_0:
	v_add_f32_e32 v88, v72, v73
	v_add_f32_e32 v89, v74, v75
	v_add_f32_e32 v88, v88, v89
	v_add_f32_e32 v89, v76, v77
	v_add_f32_e32 v91, v78, v79
	v_add_f32_e32 v89, v89, v91
	v_add_f32_e32 v88, v88, v89
	v_fmamk_f32 v88, v88, 0x3a000000, v5
	v_rsq_f32_e32 v90, v88
	s_nop 0
	s_lshl_b32 s14, s0, 13
	s_add_u32 s18, s4, s14
	s_addc_u32 s19, s5, 0
	s_add_u32 s20, s18, 0x1000
	s_addc_u32 s21, s19, 0
	v_lshlrev_b32_e32 v92, 16, v40
	v_and_b32_e32 v93, 0xffff0000, v40
	v_lshlrev_b32_e32 v94, 16, v41
	v_and_b32_e32 v95, 0xffff0000, v41
	v_pk_mul_f32 v[92:93], v[90:91], v[92:93] op_sel_hi:[0,1]
	v_pk_mul_f32 v[94:95], v[90:91], v[94:95] op_sel_hi:[0,1]
	v_pk_mul_f32 v[92:93], v[8:9], v[92:93]
	v_pk_mul_f32 v[94:95], v[10:11], v[94:95]
	global_store_dwordx4 v3, v[92:95], s[18:19]
	v_lshlrev_b32_e32 v96, 16, v42
	v_and_b32_e32 v97, 0xffff0000, v42
	v_lshlrev_b32_e32 v98, 16, v43
	v_and_b32_e32 v99, 0xffff0000, v43
	v_pk_mul_f32 v[96:97], v[90:91], v[96:97] op_sel_hi:[0,1]
	v_pk_mul_f32 v[98:99], v[90:91], v[98:99] op_sel_hi:[0,1]
	v_pk_mul_f32 v[96:97], v[12:13], v[96:97]
	v_pk_mul_f32 v[98:99], v[14:15], v[98:99]
	global_store_dwordx4 v3, v[96:99], s[18:19] offset:1024
	v_lshlrev_b32_e32 v92, 16, v44
	v_and_b32_e32 v93, 0xffff0000, v44
	v_lshlrev_b32_e32 v94, 16, v45
	v_and_b32_e32 v95, 0xffff0000, v45
	v_pk_mul_f32 v[92:93], v[90:91], v[92:93] op_sel_hi:[0,1]
	v_pk_mul_f32 v[94:95], v[90:91], v[94:95] op_sel_hi:[0,1]
	v_pk_mul_f32 v[92:93], v[16:17], v[92:93]
	v_pk_mul_f32 v[94:95], v[18:19], v[94:95]
	global_store_dwordx4 v3, v[92:95], s[18:19] offset:2048
	v_lshlrev_b32_e32 v96, 16, v46
	v_and_b32_e32 v97, 0xffff0000, v46
	v_lshlrev_b32_e32 v98, 16, v47
	v_and_b32_e32 v99, 0xffff0000, v47
	v_pk_mul_f32 v[96:97], v[90:91], v[96:97] op_sel_hi:[0,1]
	v_pk_mul_f32 v[98:99], v[90:91], v[98:99] op_sel_hi:[0,1]
	v_pk_mul_f32 v[96:97], v[20:21], v[96:97]
	v_pk_mul_f32 v[98:99], v[22:23], v[98:99]
	global_store_dwordx4 v3, v[96:99], s[18:19] offset:3072
	v_lshlrev_b32_e32 v92, 16, v48
	v_and_b32_e32 v93, 0xffff0000, v48
	v_lshlrev_b32_e32 v94, 16, v49
	v_and_b32_e32 v95, 0xffff0000, v49
	v_pk_mul_f32 v[92:93], v[90:91], v[92:93] op_sel_hi:[0,1]
	v_pk_mul_f32 v[94:95], v[90:91], v[94:95] op_sel_hi:[0,1]
	v_pk_mul_f32 v[92:93], v[24:25], v[92:93]
	v_pk_mul_f32 v[94:95], v[26:27], v[94:95]
	global_store_dwordx4 v3, v[92:95], s[20:21]
	v_lshlrev_b32_e32 v96, 16, v50
	v_and_b32_e32 v97, 0xffff0000, v50
	v_lshlrev_b32_e32 v98, 16, v51
	v_and_b32_e32 v99, 0xffff0000, v51
	v_pk_mul_f32 v[96:97], v[90:91], v[96:97] op_sel_hi:[0,1]
	v_pk_mul_f32 v[98:99], v[90:91], v[98:99] op_sel_hi:[0,1]
	v_pk_mul_f32 v[96:97], v[28:29], v[96:97]
	v_pk_mul_f32 v[98:99], v[30:31], v[98:99]
	global_store_dwordx4 v3, v[96:99], s[20:21] offset:1024
	v_lshlrev_b32_e32 v92, 16, v52
	v_and_b32_e32 v93, 0xffff0000, v52
	v_lshlrev_b32_e32 v94, 16, v53
	v_and_b32_e32 v95, 0xffff0000, v53
	v_pk_mul_f32 v[92:93], v[90:91], v[92:93] op_sel_hi:[0,1]
	v_pk_mul_f32 v[94:95], v[90:91], v[94:95] op_sel_hi:[0,1]
	v_pk_mul_f32 v[92:93], v[32:33], v[92:93]
	v_pk_mul_f32 v[94:95], v[34:35], v[94:95]
	global_store_dwordx4 v3, v[92:95], s[20:21] offset:2048
	v_lshlrev_b32_e32 v96, 16, v54
	v_and_b32_e32 v97, 0xffff0000, v54
	v_lshlrev_b32_e32 v98, 16, v55
	v_and_b32_e32 v99, 0xffff0000, v55
	v_pk_mul_f32 v[96:97], v[90:91], v[96:97] op_sel_hi:[0,1]
	v_pk_mul_f32 v[98:99], v[90:91], v[98:99] op_sel_hi:[0,1]
	v_pk_mul_f32 v[96:97], v[36:37], v[96:97]
	v_pk_mul_f32 v[98:99], v[38:39], v[98:99]
	global_store_dwordx4 v3, v[96:99], s[20:21] offset:3072
	s_add_i32 s2, s1, s10
	s_cmpk_gt_i32 s2, 0x3fff
	s_cbranch_scc1 .Lfn_nold_0
	s_lshl_b32 s14, s2, 5
	s_add_u32 s16, s22, s14
	s_addc_u32 s17, s23, 0
	s_lshl_b32 s14, s2, 12
	s_add_u32 s18, s6, s14
	s_addc_u32 s19, s7, 0
	global_load_dwordx4 v[72:75], v4, s[16:17]
	global_load_dwordx4 v[76:79], v4, s[16:17] offset:16
	global_load_dwordx2 v[40:41], v2, s[18:19]
	global_load_dwordx2 v[42:43], v2, s[18:19] offset:512
	global_load_dwordx2 v[44:45], v2, s[18:19] offset:1024
	global_load_dwordx2 v[46:47], v2, s[18:19] offset:1536
	global_load_dwordx2 v[48:49], v2, s[18:19] offset:2048
	global_load_dwordx2 v[50:51], v2, s[18:19] offset:2560
	global_load_dwordx2 v[52:53], v2, s[18:19] offset:3072
	global_load_dwordx2 v[54:55], v2, s[18:19] offset:3584
.Lfn_nold_0:
	s_mov_b32 s0, s1
	s_cmpk_gt_i32 s0, 0x3fff
	s_cbranch_scc1 .Lfn_sample
.Lfn_body1:
	s_add_i32 s1, s0, s10
	s_cmpk_gt_i32 s1, 0x3fff
	s_cbranch_scc1 .Lfn_w0_1
	s_waitcnt vmcnt(18)
	s_branch .Lfn_wd_1

; __device__ __forceinline__ float row_scale_any(const float* ssq, const float* ssqS, int row) { return row < MP ? pg8::row_scale(ssq, row) : sk::row_scale_s(ssqS, row - MP); }
; __device__ __forceinline__ f32x4 ldx4(const bf16* p) { const u32x2 w = *(const u32x2*)p; return (f32x4){__uint_as_float(w.x << 16), __uint_as_float(w.x & 0xffff0000u), __uint_as_float(w.y << 16), __uint_as_float(w.y & 0xffff0000u)}; }
; __device__ __forceinline__ float row_scale(const float* ssq, int row) { const f32x4 a = *(const f32x4*)(ssq + (size_t)row * 8), b = *(const f32x4*)(ssq + (size_t)row * 8 + 4);
;     return __builtin_amdgcn_rsqf((((a[0] + a[1]) + (a[2] + a[3])) + ((b[0] + b[1]) + (b[2] + b[3]))) * (1.0f / 2048.0f) + 1e-6f); }
; __global__ void __launch_bounds__(512, 2) fwd_kernel(Args a) {
;     ...
;         for (int m = gw; m < M; m += ngw) { const float rs = row_scale_any(ssq, SSQS + (size_t)8 * 16384, m); float* dst = m < MP ? out + OFF_Y_P + (size_t)m * D : out + OFF_Y_S + (size_t)(m - MP) * D;
; #pragma unroll
;             for (int j = 0; j < 8; ++j) { const int c = j * 256 + lane * 4; *(f32x4*)(dst + c) = ldx4(XB + (size_t)m * D + c) * rs * *(const f32x4*)(gf + c); } } }
.Lfn_wd_1:
	v_add_f32_e32 v88, v80, v81
	v_add_f32_e32 v89, v82, v83
	v_add_f32_e32 v88, v88, v89
	v_add_f32_e32 v89, v84, v85
	v_add_f32_e32 v91, v86, v87
	v_add_f32_e32 v89, v89, v91
	v_add_f32_e32 v88, v88, v89
	v_fmamk_f32 v88, v88, 0x3a000000, v5
	v_rsq_f32_e32 v90, v88
	s_nop 0
	s_lshl_b32 s14, s0, 13
	s_add_u32 s18, s4, s14
	s_addc_u32 s19, s5, 0
	s_add_u32 s20, s18, 0x1000
	s_addc_u32 s21, s19, 0
	v_lshlrev_b32_e32 v92, 16, v56
	v_and_b32_e32 v93, 0xffff0000, v56
	v_lshlrev_b32_e32 v94, 16, v57
	v_and_b32_e32 v95, 0xffff0000, v57
	v_pk_mul_f32 v[92:93], v[90:91], v[92:93] op_sel_hi:[0,1]
	v_pk_mul_f32 v[94:95], v[90:91], v[94:95] op_sel_hi:[0,1]
	v_pk_mul_f32 v[92:93], v[8:9], v[92:93]
	v_pk_mul_f32 v[94:95], v[10:11], v[94:95]
	global_store_dwordx4 v3, v[92:95], s[18:19]
	v_lshlrev_b32_e32 v96, 16, v58
	v_and_b32_e32 v97, 0xffff0000, v58
	v_lshlrev_b32_e32 v98, 16, v59
	v_and_b32_e32 v99, 0xffff0000, v59
	v_pk_mul_f32 v[96:97], v[90:91], v[96:97] op_sel_hi:[0,1]
	v_pk_mul_f32 v[98:99], v[90:91], v[98:99] op_sel_hi:[0,1]
	v_pk_mul_f32 v[96:97], v[12:13], v[96:97]
	v_pk_mul_f32 v[98:99], v[14:15], v[98:99]
	global_store_dwordx4 v3, v[96:99], s[18:19] offset:1024
	v_lshlrev_b32_e32 v92, 16, v60
	v_and_b32_e32 v93, 0xffff0000, v60
	v_lshlrev_b32_e32 v94, 16, v61
	v_and_b32_e32 v95, 0xffff0000, v61
	v_pk_mul_f32 v[92:93], v[90:91], v[92:93] op_sel_hi:[0,1]
	v_pk_mul_f32 v[94:95], v[90:91], v[94:95] op_sel_hi:[0,1]
	v_pk_mul_f32 v[92:93], v[16:17], v[92:93]
	v_pk_mul_f32 v[94:95], v[18:19], v[94:95]
	global_store_dwordx4 v3, v[92:95], s[18:19] offset:2048
	v_lshlrev_b32_e32 v96, 16, v62
	v_and_b32_e32 v97, 0xffff0000, v62
	v_lshlrev_b32_e32 v98, 16, v63
	v_and_b32_e32 v99, 0xffff0000, v63
	v_pk_mul_f32 v[96:97], v[90:91], v[96:97] op_sel_hi:[0,1]
	v_pk_mul_f32 v[98:99], v[90:91], v[98:99] op_sel_hi:[0,1]
	v_pk_mul_f32 v[96:97], v[20:21], v[96:97]
	v_pk_mul_f32 v[98:99], v[22:23], v[98:99]
	global_store_dwordx4 v3, v[96:99], s[18:19] offset:3072
	v_lshlrev_b32_e32 v92, 16, v64
	v_and_b32_e32 v93, 0xffff0000, v64
	v_lshlrev_b32_e32 v94, 16, v65
	v_and_b32_e32 v95, 0xffff0000, v65
	v_pk_mul_f32 v[92:93], v[90:91], v[92:93] op_sel_hi:[0,1]
	v_pk_mul_f32 v[94:95], v[90:91], v[94:95] op_sel_hi:[0,1]
	v_pk_mul_f32 v[92:93], v[24:25], v[92:93]
	v_pk_mul_f32 v[94:95], v[26:27], v[94:95]
	global_store_dwordx4 v3, v[92:95], s[20:21]
	v_lshlrev_b32_e32 v96, 16, v66
	v_and_b32_e32 v97, 0xffff0000, v66
	v_lshlrev_b32_e32 v98, 16, v67
	v_and_b32_e32 v99, 0xffff0000, v67
	v_pk_mul_f32 v[96:97], v[90:91], v[96:97] op_sel_hi:[0,1]
	v_pk_mul_f32 v[98:99], v[90:91], v[98:99] op_sel_hi:[0,1]
	v_pk_mul_f32 v[96:97], v[28:29], v[96:97]
	v_pk_mul_f32 v[98:99], v[30:31], v[98:99]
	global_store_dwordx4 v3, v[96:99], s[20:21] offset:1024
	v_lshlrev_b32_e32 v92, 16, v68
	v_and_b32_e32 v93, 0xffff0000, v68
	v_lshlrev_b32_e32 v94, 16, v69
	v_and_b32_e32 v95, 0xffff0000, v69
	v_pk_mul_f32 v[92:93], v[90:91], v[92:93] op_sel_hi:[0,1]
	v_pk_mul_f32 v[94:95], v[90:91], v[94:95] op_sel_hi:[0,1]
	v_pk_mul_f32 v[92:93], v[32:33], v[92:93]
	v_pk_mul_f32 v[94:95], v[34:35], v[94:95]
	global_store_dwordx4 v3, v[92:95], s[20:21] offset:2048
	v_lshlrev_b32_e32 v96, 16, v70
	v_and_b32_e32 v97, 0xffff0000, v70
	v_lshlrev_b32_e32 v98, 16, v71
	v_and_b32_e32 v99, 0xffff0000, v71
	v_pk_mul_f32 v[96:97], v[90:91], v[96:97] op_sel_hi:[0,1]
	v_pk_mul_f32 v[98:99], v[90:91], v[98:99] op_sel_hi:[0,1]
	v_pk_mul_f32 v[96:97], v[36:37], v[96:97]
	v_pk_mul_f32 v[98:99], v[38:39], v[98:99]
	global_store_dwordx4 v3, v[96:99], s[20:21] offset:3072
	s_add_i32 s2, s1, s10
	s_cmpk_gt_i32 s2, 0x3fff
	s_cbranch_scc1 .Lfn_nold_1
	s_lshl_b32 s14, s2, 5
	s_add_u32 s16, s22, s14
	s_addc_u32 s17, s23, 0
	s_lshl_b32 s14, s2, 12
	s_add_u32 s18, s6, s14
	s_addc_u32 s19, s7, 0
	global_load_dwordx4 v[80:83], v4, s[16:17]
	global_load_dwordx4 v[84:87], v4, s[16:17] offset:16
	global_load_dwordx2 v[56:57], v2, s[18:19]
	global_load_dwordx2 v[58:59], v2, s[18:19] offset:512
	global_load_dwordx2 v[60:61], v2, s[18:19] offset:1024
	global_load_dwordx2 v[62:63], v2, s[18:19] offset:1536
	global_load_dwordx2 v[64:65], v2, s[18:19] offset:2048
	global_load_dwordx2 v[66:67], v2, s[18:19] offset:2560
	global_load_dwordx2 v[68:69], v2, s[18:19] offset:3072
	global_load_dwordx2 v[70:71], v2, s[18:19] offset:3584
.Lfn_nold_1:
	s_mov_b32 s0, s1
	s_cmpk_gt_i32 s0, 0x3fff
	s_cbranch_scc1 .Lfn_sample
	s_branch .Lfn_loop
; __device__ __forceinline__ float row_scale_any(const float* ssq, const float* ssqS, int row) { return row < MP ? pg8::row_scale(ssq, row) : sk::row_scale_s(ssqS, row - MP); }
; __device__ __forceinline__ f32x4 ldx4(const bf16* p) { const u32x2 w = *(const u32x2*)p; return (f32x4){__uint_as_float(w.x << 16), __uint_as_float(w.x & 0xffff0000u), __uint_as_float(w.y << 16), __uint_as_float(w.y & 0xffff0000u)}; }
; #pragma unroll
;     for (int i = 0; i < 16; ++i) { const f32x4 a = *(const f32x4*)(ssqS + (size_t)row * 64 + 4 * i); t += (a[0] + a[1]) + (a[2] + a[3]); }
;     return __builtin_amdgcn_rsqf(t * (1.0f / 2048.0f) + 1e-6f); }
; __global__ void __launch_bounds__(512, 2) fwd_kernel(Args a) {
;     ...
;         for (int m = gw; m < M; m += ngw) { const float rs = row_scale_any(ssq, SSQS + (size_t)8 * 16384, m); float* dst = m < MP ? out + OFF_Y_P + (size_t)m * D : out + OFF_Y_S + (size_t)(m - MP) * D;
; #pragma unroll
;             for (int j = 0; j < 8; ++j) { const int c = j * 256 + lane * 4; *(f32x4*)(dst + c) = ldx4(XB + (size_t)m * D + c) * rs * *(const f32x4*)(gf + c); } } }
.Lfn_sample:
	s_cmpk_gt_i32 s0, 0x40ff
	s_cbranch_scc1 .LBB0_2890
	s_add_i32 s14, s0, 0xffffc000
	s_lshl_b32 s14, s14, 8
	s_add_u32 s16, s24, s14
	s_addc_u32 s17, s25, 0
	s_lshl_b32 s14, s0, 12
	s_add_u32 s18, s6, s14
	s_addc_u32 s19, s7, 0
	global_load_dwordx4 v[72:75], v6, s[16:17]
	global_load_dwordx2 v[40:41], v2, s[18:19]
	global_load_dwordx2 v[42:43], v2, s[18:19] offset:512
	global_load_dwordx2 v[44:45], v2, s[18:19] offset:1024
	global_load_dwordx2 v[46:47], v2, s[18:19] offset:1536
	global_load_dwordx2 v[48:49], v2, s[18:19] offset:2048
	global_load_dwordx2 v[50:51], v2, s[18:19] offset:2560
	global_load_dwordx2 v[52:53], v2, s[18:19] offset:3072
	global_load_dwordx2 v[54:55], v2, s[18:19] offset:3584
	s_waitcnt vmcnt(0)
	v_add_f32_e32 v88, v72, v73
	v_add_f32_e32 v89, v74, v75
	v_add_f32_e32 v88, v88, v89
	v_mov_b32_e32 v89, 0
	v_readlane_b32 s32, v88, 0
	v_readlane_b32 s33, v88, 1
	v_readlane_b32 s34, v88, 2
	v_readlane_b32 s35, v88, 3
	v_readlane_b32 s36, v88, 4
	v_readlane_b32 s37, v88, 5
	v_readlane_b32 s38, v88, 6
	v_readlane_b32 s39, v88, 7
	v_readlane_b32 s40, v88, 8
	v_readlane_b32 s41, v88, 9
	v_readlane_b32 s42, v88, 10
	v_readlane_b32 s43, v88, 11
	v_readlane_b32 s44, v88, 12
	v_readlane_b32 s45, v88, 13
	v_readlane_b32 s46, v88, 14
	v_readlane_b32 s47, v88, 15
	v_add_f32_e32 v89, s32, v89
	v_add_f32_e32 v89, s33, v89
	v_add_f32_e32 v89, s34, v89
	v_add_f32_e32 v89, s35, v89
	v_add_f32_e32 v89, s36, v89
	v_add_f32_e32 v89, s37, v89
	v_add_f32_e32 v89, s38, v89
	v_add_f32_e32 v89, s39, v89
	v_add_f32_e32 v89, s40, v89
	v_add_f32_e32 v89, s41, v89
	v_add_f32_e32 v89, s42, v89
	v_add_f32_e32 v89, s43, v89
	v_add_f32_e32 v89, s44, v89
	v_add_f32_e32 v89, s45, v89
	v_add_f32_e32 v89, s46, v89
	v_add_f32_e32 v89, s47, v89
	v_fmamk_f32 v88, v89, 0x3a000000, v5
	v_rsq_f32_e32 v90, v88
	s_nop 0
	s_lshl_b32 s14, s0, 13
	s_add_u32 s18, s4, s14
	s_addc_u32 s19, s5, 0
	s_add_u32 s20, s18, 0x1000
	s_addc_u32 s21, s19, 0
	v_lshlrev_b32_e32 v92, 16, v40
	v_and_b32_e32 v93, 0xffff0000, v40
	v_lshlrev_b32_e32 v94, 16, v41
	v_and_b32_e32 v95, 0xffff0000, v41
	v_pk_mul_f32 v[92:93], v[90:91], v[92:93] op_sel_hi:[0,1]
	v_pk_mul_f32 v[94:95], v[90:91], v[94:95] op_sel_hi:[0,1]
	v_pk_mul_f32 v[92:93], v[8:9], v[92:93]
	v_pk_mul_f32 v[94:95], v[10:11], v[94:95]
	global_store_dwordx4 v3, v[92:95], s[18:19]
	v_lshlrev_b32_e32 v96, 16, v42
	v_and_b32_e32 v97, 0xffff0000, v42
	v_lshlrev_b32_e32 v98, 16, v43
	v_and_b32_e32 v99, 0xffff0000, v43
	v_pk_mul_f32 v[96:97], v[90:91], v[96:97] op_sel_hi:[0,1]
	v_pk_mul_f32 v[98:99], v[90:91], v[98:99] op_sel_hi:[0,1]
	v_pk_mul_f32 v[96:97], v[12:13], v[96:97]
	v_pk_mul_f32 v[98:99], v[14:15], v[98:99]
	global_store_dwordx4 v3, v[96:99], s[18:19] offset:1024
	v_lshlrev_b32_e32 v92, 16, v44
	v_and_b32_e32 v93, 0xffff0000, v44
	v_lshlrev_b32_e32 v94, 16, v45
	v_and_b32_e32 v95, 0xffff0000, v45
	v_pk_mul_f32 v[92:93], v[90:91], v[92:93] op_sel_hi:[0,1]
	v_pk_mul_f32 v[94:95], v[90:91], v[94:95] op_sel_hi:[0,1]
	v_pk_mul_f32 v[92:93], v[16:17], v[92:93]
	v_pk_mul_f32 v[94:95], v[18:19], v[94:95]
	global_store_dwordx4 v3, v[92:95], s[18:19] offset:2048
	v_lshlrev_b32_e32 v96, 16, v46
	v_and_b32_e32 v97, 0xffff0000, v46
	v_lshlrev_b32_e32 v98, 16, v47
	v_and_b32_e32 v99, 0xffff0000, v47
	v_pk_mul_f32 v[96:97], v[90:91], v[96:97] op_sel_hi:[0,1]
	v_pk_mul_f32 v[98:99], v[90:91], v[98:99] op_sel_hi:[0,1]
	v_pk_mul_f32 v[96:97], v[20:21], v[96:97]
	v_pk_mul_f32 v[98:99], v[22:23], v[98:99]
	global_store_dwordx4 v3, v[96:99], s[18:19] offset:3072
	v_lshlrev_b32_e32 v92, 16, v48
	v_and_b32_e32 v93, 0xffff0000, v48
	v_lshlrev_b32_e32 v94, 16, v49
	v_and_b32_e32 v95, 0xffff0000, v49
	v_pk_mul_f32 v[92:93], v[90:91], v[92:93] op_sel_hi:[0,1]
	v_pk_mul_f32 v[94:95], v[90:91], v[94:95] op_sel_hi:[0,1]
	v_pk_mul_f32 v[92:93], v[24:25], v[92:93]
	v_pk_mul_f32 v[94:95], v[26:27], v[94:95]
	global_store_dwordx4 v3, v[92:95], s[20:21]
	v_lshlrev_b32_e32 v96, 16, v50
	v_and_b32_e32 v97, 0xffff0000, v50
	v_lshlrev_b32_e32 v98, 16, v51
	v_and_b32_e32 v99, 0xffff0000, v51
	v_pk_mul_f32 v[96:97], v[90:91], v[96:97] op_sel_hi:[0,1]
	v_pk_mul_f32 v[98:99], v[90:91], v[98:99] op_sel_hi:[0,1]
	v_pk_mul_f32 v[96:97], v[28:29], v[96:97]
	v_pk_mul_f32 v[98:99], v[30:31], v[98:99]
	global_store_dwordx4 v3, v[96:99], s[20:21] offset:1024
	v_lshlrev_b32_e32 v92, 16, v52
	v_and_b32_e32 v93, 0xffff0000, v52
	v_lshlrev_b32_e32 v94, 16, v53
	v_and_b32_e32 v95, 0xffff0000, v53
	v_pk_mul_f32 v[92:93], v[90:91], v[92:93] op_sel_hi:[0,1]
	v_pk_mul_f32 v[94:95], v[90:91], v[94:95] op_sel_hi:[0,1]
	v_pk_mul_f32 v[92:93], v[32:33], v[92:93]
	v_pk_mul_f32 v[94:95], v[34:35], v[94:95]
	global_store_dwordx4 v3, v[92:95], s[20:21] offset:2048
	v_lshlrev_b32_e32 v96, 16, v54
	v_and_b32_e32 v97, 0xffff0000, v54
	v_lshlrev_b32_e32 v98, 16, v55
	v_and_b32_e32 v99, 0xffff0000, v55
	v_pk_mul_f32 v[96:97], v[90:91], v[96:97] op_sel_hi:[0,1]
	v_pk_mul_f32 v[98:99], v[90:91], v[98:99] op_sel_hi:[0,1]
	v_pk_mul_f32 v[96:97], v[36:37], v[96:97]
	v_pk_mul_f32 v[98:99], v[38:39], v[98:99]
	global_store_dwordx4 v3, v[96:99], s[20:21] offset:3072
	s_add_i32 s0, s0, s10
	s_branch .Lfn_sample
